# GEMM K-loops: deleted the mid-segment s_setprio 0/1 flip pairs (one raise per 32-MFMA compute segment kept)
# speedup vs baseline: 1.0020x; 1.0002x over previous
; #define PG8_STAGE(bufoff, gbase, voff) do { _Pragma("unroll") for (int _i = 0; _i < 2; ++_i) \
;         __builtin_amdgcn_global_load_lds((const unsigned*)((const char*)(gbase) + (voff)[_i]), (PG8_LAS unsigned*)(lds + (bufoff) + ldsw + _i * 8192), 16, 0, 0); } while (0)
; #define PG8_LDA(dst, b, h) do { _Pragma("unroll") for (int m = 0; m < 4; ++m) _Pragma("unroll") for (int k = 0; k < 2; ++k) dst[m][k] = *(const PG8_LAS bf16x8*)(lds + PG8_SA(b, h) + aoff + m * 2048 + k * 1024); } while (0)
; #define PG8_LDB(dst, b, h) do { _Pragma("unroll") for (int n = 0; n < 2; ++n) _Pragma("unroll") for (int k = 0; k < 2; ++k) dst[n][k] = *(const PG8_LAS bf16x8*)(lds + PG8_SB(b, h) + boff + n * 2048 + k * 1024); } while (0)
; #define PG8_MMA(ai, bj, At, Bt) do { __builtin_amdgcn_s_setprio(1); _Pragma("unroll") for (int m = 0; m < 4; ++m) _Pragma("unroll") for (int n = 0; n < 2; ++n) _Pragma("unroll") for (int k = 0; k < 2; ++k) \
;         acc[ai][bj][m][n] = __builtin_amdgcn_mfma_f32_16x16x32_bf16(Bt[n][k], At[m][k], acc[ai][bj][m][n], 0, 0, 0); __builtin_amdgcn_s_setprio(0); } while (0)
; #define PG8_WAIT_V(n) asm volatile("s_waitcnt vmcnt(" #n ")" ::: "memory")
; #define PG8_WAIT_L(n) asm volatile("s_waitcnt lgkmcnt(" #n ")" ::: "memory")
; #define PG8_BAR __builtin_amdgcn_s_barrier()
; #define PG8_SCHED __builtin_amdgcn_sched_barrier(0)
; template <class Epi, class Sched, bool ALIGN_EPI = false, bool SP2 = false>
; __device__ __forceinline__ void gemm_phase(PG8_LAS unsigned char* lds, const Gemm g, const Sched& S, const Epi& E) {
;     ...
;             PG8_LDB(B0, 0, 0); PG8_LDB(B1, 0, 1); PG8_SCHED; PG8_LDA(At, 0, 0); PG8_STAGE(PG8_SA(1, 1), a1 + hstep, voffA);
;             PG8_WAIT_V(8); PG8_WAIT_L(0); PG8_BAR; PG8_MMA(0, 0, At, B0); PG8_MMA(0, 1, At, B1); PG8_BAR; PG8_SCHED;
;             PG8_LDA(At, 0, 1); PG8_STAGE(PG8_SB(0, 0), b2, voffB); PG8_STAGE(PG8_SB(0, 1), b2 + hstep, voffB); PG8_STAGE(PG8_SA(0, 0), a2, voffA);
;             PG8_WAIT_V(8); PG8_WAIT_L(0); PG8_BAR; PG8_MMA(1, 0, At, B0); PG8_MMA(1, 1, At, B1); PG8_BAR; PG8_SCHED;
.LBB0_1201:
	s_add_i32 s16, s15, 2
	s_add_u32 s18, s60, 0xfff80080
	s_addc_u32 s19, s61, -1
	s_add_i32 s25, 0, 0x10000
	s_cmp_eq_u32 s77, s15
	s_cselect_b32 s65, s2, s19
	s_cselect_b32 s64, s3, s18
	v_add_u32_e32 v154, s25, v157
	s_cselect_b32 s63, s8, s14
	s_cselect_b32 s62, s9, s12
	s_add_i32 s15, 0, 0x14000
	ds_read_b128 v[146:149], v154
	ds_read_b128 v[150:153], v154 offset:1024
	ds_read_b128 v[162:165], v154 offset:2048
	ds_read_b128 v[166:169], v154 offset:3072
	v_add_u32_e32 v154, s15, v157
	ds_read_b128 v[170:173], v154
	ds_read_b128 v[174:177], v154 offset:1024
	ds_read_b128 v[178:181], v154 offset:2048
	ds_read_b128 v[186:189], v154 offset:3072
	v_lshl_add_u64 v[154:155], s[60:61], 0, v[144:145]
	s_add_i32 m0, s59, 0xc000
	ds_read_b128 v[190:193], v161
	ds_read_b128 v[194:197], v161 offset:1024
	ds_read_b128 v[198:201], v161 offset:2048
	ds_read_b128 v[202:205], v161 offset:3072
	ds_read_b128 v[208:211], v161 offset:4096
	ds_read_b128 v[212:215], v161 offset:5120
	ds_read_b128 v[216:219], v161 offset:6144
	ds_read_b128 v[220:223], v161 offset:7168
	global_load_lds_dwordx4 v[154:155], off
	v_lshl_add_u64 v[154:155], s[60:61], 0, v[140:141]
	s_add_i32 m0, s59, 0xe000
	s_nop 0
	global_load_lds_dwordx4 v[154:155], off
	s_waitcnt vmcnt(8)
	s_waitcnt lgkmcnt(0)
	s_barrier
	s_setprio 1
	s_waitcnt lgkmcnt(0)
	v_mfma_f32_16x16x32_bf16 v[130:133], v[146:149], v[190:193], v[130:133]
	v_mfma_f32_16x16x32_bf16 v[126:129], v[162:165], v[190:193], v[126:129]
	v_mfma_f32_16x16x32_bf16 v[114:117], v[146:149], v[198:201], v[114:117]
	v_mfma_f32_16x16x32_bf16 v[110:113], v[162:165], v[198:201], v[110:113]
	v_mfma_f32_16x16x32_bf16 v[94:97], v[146:149], v[208:211], v[94:97]
	v_mfma_f32_16x16x32_bf16 v[90:93], v[162:165], v[208:211], v[90:93]
	v_mfma_f32_16x16x32_bf16 v[78:81], v[146:149], v[216:219], v[78:81]
	v_mfma_f32_16x16x32_bf16 v[74:77], v[162:165], v[216:219], v[74:77]
	v_mfma_f32_16x16x32_bf16 v[130:133], v[150:153], v[194:197], v[130:133]
	v_mfma_f32_16x16x32_bf16 v[126:129], v[166:169], v[194:197], v[126:129]
	v_mfma_f32_16x16x32_bf16 v[114:117], v[150:153], v[202:205], v[114:117]
	v_mfma_f32_16x16x32_bf16 v[110:113], v[166:169], v[202:205], v[110:113]
	v_mfma_f32_16x16x32_bf16 v[94:97], v[150:153], v[212:215], v[94:97]
	v_mfma_f32_16x16x32_bf16 v[90:93], v[166:169], v[212:215], v[90:93]
	v_mfma_f32_16x16x32_bf16 v[78:81], v[150:153], v[220:223], v[78:81]
	v_mfma_f32_16x16x32_bf16 v[74:77], v[166:169], v[220:223], v[74:77]
	v_mfma_f32_16x16x32_bf16 v[122:125], v[170:173], v[190:193], v[122:125]
	v_mfma_f32_16x16x32_bf16 v[118:121], v[178:181], v[190:193], v[118:121]
	v_mfma_f32_16x16x32_bf16 v[106:109], v[170:173], v[198:201], v[106:109]
	v_mfma_f32_16x16x32_bf16 v[102:105], v[178:181], v[198:201], v[102:105]
	v_mfma_f32_16x16x32_bf16 v[86:89], v[170:173], v[208:211], v[86:89]
	v_mfma_f32_16x16x32_bf16 v[82:85], v[178:181], v[208:211], v[82:85]
	v_mfma_f32_16x16x32_bf16 v[70:73], v[170:173], v[216:219], v[70:73]
	v_mfma_f32_16x16x32_bf16 v[66:69], v[178:181], v[216:219], v[66:69]
	v_mfma_f32_16x16x32_bf16 v[122:125], v[174:177], v[194:197], v[122:125]
	v_mfma_f32_16x16x32_bf16 v[118:121], v[186:189], v[194:197], v[118:121]
	v_mfma_f32_16x16x32_bf16 v[106:109], v[174:177], v[202:205], v[106:109]
	v_mfma_f32_16x16x32_bf16 v[102:105], v[186:189], v[202:205], v[102:105]
	v_mfma_f32_16x16x32_bf16 v[86:89], v[174:177], v[212:215], v[86:89]
	v_mfma_f32_16x16x32_bf16 v[82:85], v[186:189], v[212:215], v[82:85]
	v_mfma_f32_16x16x32_bf16 v[70:73], v[174:177], v[220:223], v[70:73]
	v_mfma_f32_16x16x32_bf16 v[66:69], v[186:189], v[220:223], v[66:69]
	s_setprio 0
	s_barrier
	s_add_i32 s18, s25, s67
	v_lshl_add_u64 v[154:155], s[62:63], 0, v[0:1]
	s_mov_b32 m0, s18
	ds_read_b128 v[190:193], v161 offset:16384
	ds_read_b128 v[194:197], v161 offset:17408
	ds_read_b128 v[198:201], v161 offset:18432
	ds_read_b128 v[202:205], v161 offset:19456
	ds_read_b128 v[208:211], v161 offset:20480
	ds_read_b128 v[212:215], v161 offset:21504
	ds_read_b128 v[216:219], v161 offset:22528
	ds_read_b128 v[220:223], v161 offset:23552
	global_load_lds_dwordx4 v[154:155], off
	s_add_i32 m0, s18, 0x2000
	s_add_u32 s18, s62, 0x80000
	v_lshl_add_u64 v[182:183], s[62:63], 0, v[138:139]
	s_addc_u32 s19, s63, 0
	s_add_i32 s15, s15, s67
	global_load_lds_dwordx4 v[182:183], off
	v_lshl_add_u64 v[224:225], s[18:19], 0, v[0:1]
	s_mov_b32 m0, s15
	v_lshl_add_u64 v[226:227], s[64:65], 0, v[136:137]
	global_load_lds_dwordx4 v[224:225], off
	v_lshl_add_u64 v[224:225], s[18:19], 0, v[138:139]
	s_add_i32 m0, s15, 0x2000
	s_nop 0
	global_load_lds_dwordx4 v[224:225], off
	v_lshl_add_u64 v[224:225], s[64:65], 0, v[134:135]
	s_mov_b32 m0, s59
	s_nop 0
	global_load_lds_dwordx4 v[224:225], off
	s_mov_b32 m0, s68
	s_nop 0
	global_load_lds_dwordx4 v[226:227], off
	s_waitcnt vmcnt(8)
	s_waitcnt lgkmcnt(0)
	s_barrier
; #define PG8_STAGE(bufoff, gbase, voff) do { _Pragma("unroll") for (int _i = 0; _i < 2; ++_i) \
;         __builtin_amdgcn_global_load_lds((const unsigned*)((const char*)(gbase) + (voff)[_i]), (PG8_LAS unsigned*)(lds + (bufoff) + ldsw + _i * 8192), 16, 0, 0); } while (0)
; #define PG8_LDA(dst, b, h) do { _Pragma("unroll") for (int m = 0; m < 4; ++m) _Pragma("unroll") for (int k = 0; k < 2; ++k) dst[m][k] = *(const PG8_LAS bf16x8*)(lds + PG8_SA(b, h) + aoff + m * 2048 + k * 1024); } while (0)
; #define PG8_LDB(dst, b, h) do { _Pragma("unroll") for (int n = 0; n < 2; ++n) _Pragma("unroll") for (int k = 0; k < 2; ++k) dst[n][k] = *(const PG8_LAS bf16x8*)(lds + PG8_SB(b, h) + boff + n * 2048 + k * 1024); } while (0)
; #define PG8_MMA(ai, bj, At, Bt) do { __builtin_amdgcn_s_setprio(1); _Pragma("unroll") for (int m = 0; m < 4; ++m) _Pragma("unroll") for (int n = 0; n < 2; ++n) _Pragma("unroll") for (int k = 0; k < 2; ++k) \
;         acc[ai][bj][m][n] = __builtin_amdgcn_mfma_f32_16x16x32_bf16(Bt[n][k], At[m][k], acc[ai][bj][m][n], 0, 0, 0); __builtin_amdgcn_s_setprio(0); } while (0)
; #define PG8_WAIT_V(n) asm volatile("s_waitcnt vmcnt(" #n ")" ::: "memory")
; #define PG8_WAIT_L(n) asm volatile("s_waitcnt lgkmcnt(" #n ")" ::: "memory")
; #define PG8_BAR __builtin_amdgcn_s_barrier()
; #define PG8_SCHED __builtin_amdgcn_sched_barrier(0)
; template <class Epi, class Sched, bool ALIGN_EPI = false, bool SP2 = false>
; __device__ __forceinline__ void gemm_phase(PG8_LAS unsigned char* lds, const Gemm g, const Sched& S, const Epi& E) {
;     ...
;             PG8_WAIT_V(8); PG8_WAIT_L(0); PG8_BAR; PG8_MMA(1, 0, At, B0); PG8_MMA(1, 1, At, B1); PG8_BAR; PG8_SCHED;
;             PG8_LDB(B0, 1, 0); PG8_LDB(B1, 1, 1); PG8_SCHED; PG8_LDA(At, 1, 0); PG8_STAGE(PG8_SA(0, 1), a2 + hstep, voffA);
;             PG8_WAIT_V(8); PG8_WAIT_L(0); PG8_BAR; PG8_MMA(0, 0, At, B0); PG8_MMA(0, 1, At, B1); PG8_BAR; PG8_SCHED;
	s_setprio 1
	s_waitcnt lgkmcnt(0)
	v_mfma_f32_16x16x32_bf16 v[62:65], v[146:149], v[190:193], v[62:65]
	v_mfma_f32_16x16x32_bf16 v[58:61], v[162:165], v[190:193], v[58:61]
	v_mfma_f32_16x16x32_bf16 v[46:49], v[146:149], v[198:201], v[46:49]
	v_mfma_f32_16x16x32_bf16 v[42:45], v[162:165], v[198:201], v[42:45]
	v_mfma_f32_16x16x32_bf16 v[30:33], v[146:149], v[208:211], v[30:33]
	v_mfma_f32_16x16x32_bf16 v[26:29], v[162:165], v[208:211], v[26:29]
	v_mfma_f32_16x16x32_bf16 v[14:17], v[146:149], v[216:219], v[14:17]
	v_mfma_f32_16x16x32_bf16 v[10:13], v[162:165], v[216:219], v[10:13]
	v_mfma_f32_16x16x32_bf16 v[62:65], v[150:153], v[194:197], v[62:65]
	v_mfma_f32_16x16x32_bf16 v[58:61], v[166:169], v[194:197], v[58:61]
	v_mfma_f32_16x16x32_bf16 v[46:49], v[150:153], v[202:205], v[46:49]
	v_mfma_f32_16x16x32_bf16 v[42:45], v[166:169], v[202:205], v[42:45]
	v_mfma_f32_16x16x32_bf16 v[30:33], v[150:153], v[212:215], v[30:33]
	v_mfma_f32_16x16x32_bf16 v[26:29], v[166:169], v[212:215], v[26:29]
	v_mfma_f32_16x16x32_bf16 v[14:17], v[150:153], v[220:223], v[14:17]
	v_mfma_f32_16x16x32_bf16 v[10:13], v[166:169], v[220:223], v[10:13]
	v_mfma_f32_16x16x32_bf16 v[54:57], v[170:173], v[190:193], v[54:57]
	v_mfma_f32_16x16x32_bf16 v[50:53], v[178:181], v[190:193], v[50:53]
	v_mfma_f32_16x16x32_bf16 v[38:41], v[170:173], v[198:201], v[38:41]
	v_mfma_f32_16x16x32_bf16 v[34:37], v[178:181], v[198:201], v[34:37]
	v_mfma_f32_16x16x32_bf16 v[22:25], v[170:173], v[208:211], v[22:25]
	v_mfma_f32_16x16x32_bf16 v[18:21], v[178:181], v[208:211], v[18:21]
	v_mfma_f32_16x16x32_bf16 v[6:9], v[170:173], v[216:219], v[6:9]
	v_mfma_f32_16x16x32_bf16 v[2:5], v[178:181], v[216:219], v[2:5]
	v_mfma_f32_16x16x32_bf16 v[54:57], v[174:177], v[194:197], v[54:57]
	v_mfma_f32_16x16x32_bf16 v[50:53], v[186:189], v[194:197], v[50:53]
	v_mfma_f32_16x16x32_bf16 v[38:41], v[174:177], v[202:205], v[38:41]
	v_mfma_f32_16x16x32_bf16 v[34:37], v[186:189], v[202:205], v[34:37]
	v_mfma_f32_16x16x32_bf16 v[22:25], v[174:177], v[212:215], v[22:25]
	v_mfma_f32_16x16x32_bf16 v[18:21], v[186:189], v[212:215], v[18:21]
	v_mfma_f32_16x16x32_bf16 v[6:9], v[174:177], v[220:223], v[6:9]
	v_mfma_f32_16x16x32_bf16 v[2:5], v[186:189], v[220:223], v[2:5]
	s_setprio 0
	s_barrier
	s_add_i32 s15, 0, 0x18000
	s_add_i32 s25, 0, 0x1c000
	v_add_u32_e32 v166, s15, v157
	v_add_u32_e32 v184, s25, v157
	ds_read_b128 v[146:149], v166
	ds_read_b128 v[150:153], v166 offset:1024
	ds_read_b128 v[162:165], v166 offset:2048
	ds_read_b128 v[166:169], v166 offset:3072
	ds_read_b128 v[170:173], v184
	ds_read_b128 v[174:177], v184 offset:1024
	ds_read_b128 v[178:181], v184 offset:2048
	ds_read_b128 v[186:189], v184 offset:3072
	s_add_u32 s18, s64, 0x80000
	s_addc_u32 s19, s65, 0
	s_mov_b32 m0, s69
	v_lshl_add_u64 v[230:231], s[18:19], 0, v[134:135]
	ds_read_b128 v[190:193], v161 offset:32768
	ds_read_b128 v[194:197], v161 offset:33792
	ds_read_b128 v[198:201], v161 offset:34816
	ds_read_b128 v[202:205], v161 offset:35840
	ds_read_b128 v[208:211], v161 offset:36864
	ds_read_b128 v[212:215], v161 offset:37888
	ds_read_b128 v[216:219], v161 offset:38912
	ds_read_b128 v[220:223], v161 offset:39936
	global_load_lds_dwordx4 v[230:231], off
	v_lshl_add_u64 v[230:231], s[18:19], 0, v[136:137]
	s_mov_b32 m0, s70
	s_nop 0
	global_load_lds_dwordx4 v[230:231], off
	s_waitcnt vmcnt(8)
	s_waitcnt lgkmcnt(0)
	s_barrier
	s_setprio 1
	s_waitcnt lgkmcnt(0)
	v_mfma_f32_16x16x32_bf16 v[130:133], v[146:149], v[190:193], v[130:133]
	v_mfma_f32_16x16x32_bf16 v[126:129], v[162:165], v[190:193], v[126:129]
	v_mfma_f32_16x16x32_bf16 v[114:117], v[146:149], v[198:201], v[114:117]
	v_mfma_f32_16x16x32_bf16 v[110:113], v[162:165], v[198:201], v[110:113]
	v_mfma_f32_16x16x32_bf16 v[94:97], v[146:149], v[208:211], v[94:97]
	v_mfma_f32_16x16x32_bf16 v[90:93], v[162:165], v[208:211], v[90:93]
	v_mfma_f32_16x16x32_bf16 v[78:81], v[146:149], v[216:219], v[78:81]
	v_mfma_f32_16x16x32_bf16 v[74:77], v[162:165], v[216:219], v[74:77]
	v_mfma_f32_16x16x32_bf16 v[130:133], v[150:153], v[194:197], v[130:133]
	v_mfma_f32_16x16x32_bf16 v[126:129], v[166:169], v[194:197], v[126:129]
	v_mfma_f32_16x16x32_bf16 v[114:117], v[150:153], v[202:205], v[114:117]
	v_mfma_f32_16x16x32_bf16 v[110:113], v[166:169], v[202:205], v[110:113]
	v_mfma_f32_16x16x32_bf16 v[94:97], v[150:153], v[212:215], v[94:97]
	v_mfma_f32_16x16x32_bf16 v[90:93], v[166:169], v[212:215], v[90:93]
	v_mfma_f32_16x16x32_bf16 v[78:81], v[150:153], v[220:223], v[78:81]
	v_mfma_f32_16x16x32_bf16 v[74:77], v[166:169], v[220:223], v[74:77]
	v_mfma_f32_16x16x32_bf16 v[122:125], v[170:173], v[190:193], v[122:125]
	v_mfma_f32_16x16x32_bf16 v[118:121], v[178:181], v[190:193], v[118:121]
	v_mfma_f32_16x16x32_bf16 v[106:109], v[170:173], v[198:201], v[106:109]
	v_mfma_f32_16x16x32_bf16 v[102:105], v[178:181], v[198:201], v[102:105]
	v_mfma_f32_16x16x32_bf16 v[86:89], v[170:173], v[208:211], v[86:89]
	v_mfma_f32_16x16x32_bf16 v[82:85], v[178:181], v[208:211], v[82:85]
	v_mfma_f32_16x16x32_bf16 v[70:73], v[170:173], v[216:219], v[70:73]
	v_mfma_f32_16x16x32_bf16 v[66:69], v[178:181], v[216:219], v[66:69]
	v_mfma_f32_16x16x32_bf16 v[122:125], v[174:177], v[194:197], v[122:125]
	v_mfma_f32_16x16x32_bf16 v[118:121], v[186:189], v[194:197], v[118:121]
	v_mfma_f32_16x16x32_bf16 v[106:109], v[174:177], v[202:205], v[106:109]
	v_mfma_f32_16x16x32_bf16 v[102:105], v[186:189], v[202:205], v[102:105]
	v_mfma_f32_16x16x32_bf16 v[86:89], v[174:177], v[212:215], v[86:89]
	v_mfma_f32_16x16x32_bf16 v[82:85], v[186:189], v[212:215], v[82:85]
	v_mfma_f32_16x16x32_bf16 v[70:73], v[174:177], v[220:223], v[70:73]
	v_mfma_f32_16x16x32_bf16 v[66:69], v[186:189], v[220:223], v[66:69]
	s_setprio 0
	s_barrier
; #define PG8_STAGE(bufoff, gbase, voff) do { _Pragma("unroll") for (int _i = 0; _i < 2; ++_i) \
;         __builtin_amdgcn_global_load_lds((const unsigned*)((const char*)(gbase) + (voff)[_i]), (PG8_LAS unsigned*)(lds + (bufoff) + ldsw + _i * 8192), 16, 0, 0); } while (0)
; #define PG8_LDA(dst, b, h) do { _Pragma("unroll") for (int m = 0; m < 4; ++m) _Pragma("unroll") for (int k = 0; k < 2; ++k) dst[m][k] = *(const PG8_LAS bf16x8*)(lds + PG8_SA(b, h) + aoff + m * 2048 + k * 1024); } while (0)
; #define PG8_MMA(ai, bj, At, Bt) do { __builtin_amdgcn_s_setprio(1); _Pragma("unroll") for (int m = 0; m < 4; ++m) _Pragma("unroll") for (int n = 0; n < 2; ++n) _Pragma("unroll") for (int k = 0; k < 2; ++k) \
;         acc[ai][bj][m][n] = __builtin_amdgcn_mfma_f32_16x16x32_bf16(Bt[n][k], At[m][k], acc[ai][bj][m][n], 0, 0, 0); __builtin_amdgcn_s_setprio(0); } while (0)
; #define PG8_WAIT_V(n) asm volatile("s_waitcnt vmcnt(" #n ")" ::: "memory")
; #define PG8_WAIT_L(n) asm volatile("s_waitcnt lgkmcnt(" #n ")" ::: "memory")
; #define PG8_BAR __builtin_amdgcn_s_barrier()
; #define PG8_SCHED __builtin_amdgcn_sched_barrier(0)
; template <class Epi, class Sched, bool ALIGN_EPI = false, bool SP2 = false>
; __device__ __forceinline__ void gemm_phase(PG8_LAS unsigned char* lds, const Gemm g, const Sched& S, const Epi& E) {
;     ...
;         for (int t = 0; t < nt; t += 2) {
;     ...
;             PG8_LDA(At, 1, 1); PG8_STAGE(PG8_SB(1, 0), b3, voffB); PG8_STAGE(PG8_SB(1, 1), b3 + hstep, voffB); PG8_STAGE(PG8_SA(1, 0), a3, voffA);
;             PG8_WAIT_V(8); PG8_WAIT_L(0); PG8_BAR; PG8_MMA(1, 0, At, B0); PG8_MMA(1, 1, At, B1); PG8_BAR; PG8_SCHED;
	s_add_i32 s15, s15, s67
	v_lshl_add_u64 v[154:155], v[154:155], 0, s[22:23]
	s_mov_b32 m0, s15
	ds_read_b128 v[190:193], v161 offset:49152
	ds_read_b128 v[194:197], v161 offset:50176
	ds_read_b128 v[198:201], v161 offset:51200
	ds_read_b128 v[202:205], v161 offset:52224
	ds_read_b128 v[208:211], v161 offset:53248
	ds_read_b128 v[212:215], v161 offset:54272
	ds_read_b128 v[216:219], v161 offset:55296
	ds_read_b128 v[220:223], v161 offset:56320
	global_load_lds_dwordx4 v[154:155], off
	s_add_i32 m0, s15, 0x2000
	s_add_u32 s18, s62, 0x80080
	v_lshl_add_u64 v[154:155], v[182:183], 0, s[22:23]
	s_addc_u32 s19, s63, 0
	s_add_i32 s15, s25, s67
	global_load_lds_dwordx4 v[154:155], off
	v_lshl_add_u64 v[154:155], s[18:19], 0, v[0:1]
	s_mov_b32 m0, s15
	s_nop 0
	global_load_lds_dwordx4 v[154:155], off
	v_lshl_add_u64 v[154:155], s[18:19], 0, v[138:139]
	s_add_i32 m0, s15, 0x2000
	s_nop 0
	global_load_lds_dwordx4 v[154:155], off
	v_lshl_add_u64 v[154:155], v[224:225], 0, s[22:23]
	s_mov_b32 m0, s75
	s_nop 0
	global_load_lds_dwordx4 v[154:155], off
	v_lshl_add_u64 v[154:155], v[226:227], 0, s[22:23]
	s_mov_b32 m0, s76
	s_nop 0
	global_load_lds_dwordx4 v[154:155], off
	s_waitcnt vmcnt(8)
	s_waitcnt lgkmcnt(0)
	s_barrier
	s_setprio 1
	s_waitcnt lgkmcnt(0)
	v_mfma_f32_16x16x32_bf16 v[62:65], v[146:149], v[190:193], v[62:65]
	v_mfma_f32_16x16x32_bf16 v[58:61], v[162:165], v[190:193], v[58:61]
	v_mfma_f32_16x16x32_bf16 v[46:49], v[146:149], v[198:201], v[46:49]
	v_mfma_f32_16x16x32_bf16 v[42:45], v[162:165], v[198:201], v[42:45]
	v_mfma_f32_16x16x32_bf16 v[30:33], v[146:149], v[208:211], v[30:33]
	v_mfma_f32_16x16x32_bf16 v[26:29], v[162:165], v[208:211], v[26:29]
	v_mfma_f32_16x16x32_bf16 v[14:17], v[146:149], v[216:219], v[14:17]
	v_mfma_f32_16x16x32_bf16 v[10:13], v[162:165], v[216:219], v[10:13]
	v_mfma_f32_16x16x32_bf16 v[62:65], v[150:153], v[194:197], v[62:65]
	v_mfma_f32_16x16x32_bf16 v[58:61], v[166:169], v[194:197], v[58:61]
	v_mfma_f32_16x16x32_bf16 v[46:49], v[150:153], v[202:205], v[46:49]
	v_mfma_f32_16x16x32_bf16 v[42:45], v[166:169], v[202:205], v[42:45]
	v_mfma_f32_16x16x32_bf16 v[30:33], v[150:153], v[212:215], v[30:33]
	v_mfma_f32_16x16x32_bf16 v[26:29], v[166:169], v[212:215], v[26:29]
	v_mfma_f32_16x16x32_bf16 v[14:17], v[150:153], v[220:223], v[14:17]
	v_mfma_f32_16x16x32_bf16 v[10:13], v[166:169], v[220:223], v[10:13]
	v_mfma_f32_16x16x32_bf16 v[54:57], v[170:173], v[190:193], v[54:57]
	v_mfma_f32_16x16x32_bf16 v[50:53], v[178:181], v[190:193], v[50:53]
	v_mfma_f32_16x16x32_bf16 v[38:41], v[170:173], v[198:201], v[38:41]
	v_mfma_f32_16x16x32_bf16 v[34:37], v[178:181], v[198:201], v[34:37]
	v_mfma_f32_16x16x32_bf16 v[22:25], v[170:173], v[208:211], v[22:25]
	v_mfma_f32_16x16x32_bf16 v[18:21], v[178:181], v[208:211], v[18:21]
	v_mfma_f32_16x16x32_bf16 v[6:9], v[170:173], v[216:219], v[6:9]
	v_mfma_f32_16x16x32_bf16 v[2:5], v[178:181], v[216:219], v[2:5]
	v_mfma_f32_16x16x32_bf16 v[54:57], v[174:177], v[194:197], v[54:57]
	v_mfma_f32_16x16x32_bf16 v[50:53], v[186:189], v[194:197], v[50:53]
	v_mfma_f32_16x16x32_bf16 v[38:41], v[174:177], v[202:205], v[38:41]
	v_mfma_f32_16x16x32_bf16 v[34:37], v[186:189], v[202:205], v[34:37]
	v_mfma_f32_16x16x32_bf16 v[22:25], v[174:177], v[212:215], v[22:25]
	v_mfma_f32_16x16x32_bf16 v[18:21], v[186:189], v[212:215], v[18:21]
	v_mfma_f32_16x16x32_bf16 v[6:9], v[174:177], v[220:223], v[6:9]
	v_mfma_f32_16x16x32_bf16 v[2:5], v[186:189], v[220:223], v[2:5]
	s_setprio 0
	s_barrier
	s_add_u32 s12, s12, 0x100
	s_addc_u32 s14, s14, 0
	s_add_u32 s60, s60, 0x100
	s_addc_u32 s61, s61, 0
	s_cmp_ge_u32 s16, s74
	s_mov_b32 s15, s16
	s_cbranch_scc0 .LBB0_1201
	s_and_b64 vcc, exec, s[46:47]
	s_cbranch_vccz .LBB0_1204
	s_barrier

; #define PG8_STAGE(bufoff, gbase, voff) do { _Pragma("unroll") for (int _i = 0; _i < 2; ++_i) \
;         __builtin_amdgcn_global_load_lds((const unsigned*)((const char*)(gbase) + (voff)[_i]), (PG8_LAS unsigned*)(lds + (bufoff) + ldsw + _i * 8192), 16, 0, 0); } while (0)
; #define PG8_LDA(dst, b, h) do { _Pragma("unroll") for (int m = 0; m < 4; ++m) _Pragma("unroll") for (int k = 0; k < 2; ++k) dst[m][k] = *(const PG8_LAS bf16x8*)(lds + PG8_SA(b, h) + aoff + m * 2048 + k * 1024); } while (0)
; #define PG8_LDB(dst, b, h) do { _Pragma("unroll") for (int n = 0; n < 2; ++n) _Pragma("unroll") for (int k = 0; k < 2; ++k) dst[n][k] = *(const PG8_LAS bf16x8*)(lds + PG8_SB(b, h) + boff + n * 2048 + k * 1024); } while (0)
; #define PG8_MMA(ai, bj, At, Bt) do { __builtin_amdgcn_s_setprio(1); _Pragma("unroll") for (int m = 0; m < 4; ++m) _Pragma("unroll") for (int n = 0; n < 2; ++n) _Pragma("unroll") for (int k = 0; k < 2; ++k) \
;         acc[ai][bj][m][n] = __builtin_amdgcn_mfma_f32_16x16x32_bf16(Bt[n][k], At[m][k], acc[ai][bj][m][n], 0, 0, 0); __builtin_amdgcn_s_setprio(0); } while (0)
; #define PG8_WAIT_V(n) asm volatile("s_waitcnt vmcnt(" #n ")" ::: "memory")
; #define PG8_WAIT_L(n) asm volatile("s_waitcnt lgkmcnt(" #n ")" ::: "memory")
; template <class Epi, class Sched, bool ALIGN_EPI = false, bool SP2 = false>
; __device__ __forceinline__ void gemm_phase(PG8_LAS unsigned char* lds, const Gemm g, const Sched& S, const Epi& E) {
;     ...
;             const bool last = (t == nt - 2);
;             const char* a1 = cA + (size_t)(t + 1) * kstep;
;             const char* a2 = last ? nA : cA + (size_t)(t + 2) * kstep; const char* b2 = last ? nB : cB + (size_t)(t + 2) * kstep;
;             const char* a3 = a2 + kstep; const char* b3 = b2 + kstep;
;             if (last && has_next) S.a_ready(nxt);
;             if constexpr (SP2) {
;             PG8_LDB(B0, 0, 0); PG8_LDB(B1, 0, 1); PG8_SCHED; PG8_LDA(At, 0, 0); PG8_STAGE(PG8_SA(1, 1), a1 + hstep, voffA);
;             PG8_WAIT_V(8); PG8_WAIT_L(0); PG8_BAR; PG8_MMA(0, 0, At, B0); PG8_MMA(0, 1, At, B1); PG8_BAR; PG8_SCHED;
;             PG8_LDA(At, 0, 1); PG8_STAGE(PG8_SB(0, 0), b2, voffB); PG8_STAGE(PG8_SB(0, 1), b2 + hstep, voffB); PG8_STAGE(PG8_SA(0, 0), a2, voffA);
;             PG8_WAIT_V(8); PG8_WAIT_L(0); PG8_BAR; PG8_MMA(1, 0, At, B0); PG8_MMA(1, 1, At, B1); PG8_BAR; PG8_SCHED;
.LBB0_1272:
	s_add_u32 s41, s0, 0xfff80080
	s_addc_u32 s42, s1, -1
	s_add_i32 s51, 0, 0x10000
	s_cmp_eq_u32 s19, 28
	s_cselect_b32 s59, s2, s42
	s_cselect_b32 s58, s3, s41
	v_add_u32_e32 v154, s51, v157
	s_cselect_b32 s43, s8, s18
	s_cselect_b32 s42, s12, s14
	s_add_i32 s41, 0, 0x14000
	ds_read_b128 v[146:149], v154
	ds_read_b128 v[150:153], v154 offset:1024
	ds_read_b128 v[160:163], v154 offset:2048
	ds_read_b128 v[164:167], v154 offset:3072
	v_add_u32_e32 v154, s41, v157
	ds_read_b128 v[168:171], v154
	ds_read_b128 v[172:175], v154 offset:1024
	ds_read_b128 v[176:179], v154 offset:2048
	ds_read_b128 v[180:183], v154 offset:3072
	v_lshl_add_u64 v[154:155], s[0:1], 0, v[144:145]
	s_add_i32 m0, s16, 0xc000
	ds_read_b128 v[186:189], v159
	ds_read_b128 v[190:193], v159 offset:1024
	ds_read_b128 v[194:197], v159 offset:2048
	ds_read_b128 v[198:201], v159 offset:3072
	ds_read_b128 v[202:205], v159 offset:4096
	ds_read_b128 v[208:211], v159 offset:5120
	ds_read_b128 v[212:215], v159 offset:6144
	ds_read_b128 v[216:219], v159 offset:7168
	global_load_lds_dwordx4 v[154:155], off
	v_lshl_add_u64 v[154:155], s[0:1], 0, v[140:141]
	s_add_i32 m0, s16, 0xe000
	s_nop 0
	global_load_lds_dwordx4 v[154:155], off
	s_waitcnt vmcnt(8)
	s_waitcnt lgkmcnt(0)
	s_barrier
	s_setprio 1
	s_waitcnt lgkmcnt(0)
	v_mfma_f32_16x16x32_bf16 v[130:133], v[146:149], v[186:189], v[130:133]
	v_mfma_f32_16x16x32_bf16 v[126:129], v[160:163], v[186:189], v[126:129]
	v_mfma_f32_16x16x32_bf16 v[114:117], v[146:149], v[194:197], v[114:117]
	v_mfma_f32_16x16x32_bf16 v[110:113], v[160:163], v[194:197], v[110:113]
	v_mfma_f32_16x16x32_bf16 v[94:97], v[146:149], v[202:205], v[94:97]
	v_mfma_f32_16x16x32_bf16 v[90:93], v[160:163], v[202:205], v[90:93]
	v_mfma_f32_16x16x32_bf16 v[78:81], v[146:149], v[212:215], v[78:81]
	v_mfma_f32_16x16x32_bf16 v[74:77], v[160:163], v[212:215], v[74:77]
	v_mfma_f32_16x16x32_bf16 v[130:133], v[150:153], v[190:193], v[130:133]
	v_mfma_f32_16x16x32_bf16 v[126:129], v[164:167], v[190:193], v[126:129]
	v_mfma_f32_16x16x32_bf16 v[114:117], v[150:153], v[198:201], v[114:117]
	v_mfma_f32_16x16x32_bf16 v[110:113], v[164:167], v[198:201], v[110:113]
	v_mfma_f32_16x16x32_bf16 v[94:97], v[150:153], v[208:211], v[94:97]
	v_mfma_f32_16x16x32_bf16 v[90:93], v[164:167], v[208:211], v[90:93]
	v_mfma_f32_16x16x32_bf16 v[78:81], v[150:153], v[216:219], v[78:81]
	v_mfma_f32_16x16x32_bf16 v[74:77], v[164:167], v[216:219], v[74:77]
	v_mfma_f32_16x16x32_bf16 v[122:125], v[168:171], v[186:189], v[122:125]
	v_mfma_f32_16x16x32_bf16 v[118:121], v[176:179], v[186:189], v[118:121]
	v_mfma_f32_16x16x32_bf16 v[106:109], v[168:171], v[194:197], v[106:109]
	v_mfma_f32_16x16x32_bf16 v[102:105], v[176:179], v[194:197], v[102:105]
	v_mfma_f32_16x16x32_bf16 v[86:89], v[168:171], v[202:205], v[86:89]
	v_mfma_f32_16x16x32_bf16 v[82:85], v[176:179], v[202:205], v[82:85]
	v_mfma_f32_16x16x32_bf16 v[70:73], v[168:171], v[212:215], v[70:73]
	v_mfma_f32_16x16x32_bf16 v[66:69], v[176:179], v[212:215], v[66:69]
	v_mfma_f32_16x16x32_bf16 v[122:125], v[172:175], v[190:193], v[122:125]
	v_mfma_f32_16x16x32_bf16 v[118:121], v[180:183], v[190:193], v[118:121]
	v_mfma_f32_16x16x32_bf16 v[106:109], v[172:175], v[198:201], v[106:109]
	v_mfma_f32_16x16x32_bf16 v[102:105], v[180:183], v[198:201], v[102:105]
	v_mfma_f32_16x16x32_bf16 v[86:89], v[172:175], v[208:211], v[86:89]
	v_mfma_f32_16x16x32_bf16 v[82:85], v[180:183], v[208:211], v[82:85]
	v_mfma_f32_16x16x32_bf16 v[70:73], v[172:175], v[216:219], v[70:73]
	v_mfma_f32_16x16x32_bf16 v[66:69], v[180:183], v[216:219], v[66:69]
	s_setprio 0
	s_barrier
	s_add_i32 s51, s51, s10
	v_lshl_add_u64 v[154:155], s[42:43], 0, v[0:1]
	s_mov_b32 m0, s51
	ds_read_b128 v[186:189], v159 offset:16384
	ds_read_b128 v[190:193], v159 offset:17408
	ds_read_b128 v[194:197], v159 offset:18432
	ds_read_b128 v[198:201], v159 offset:19456
	ds_read_b128 v[202:205], v159 offset:20480
	ds_read_b128 v[208:211], v159 offset:21504
	ds_read_b128 v[212:215], v159 offset:22528
	ds_read_b128 v[216:219], v159 offset:23552
	global_load_lds_dwordx4 v[154:155], off
	s_add_i32 m0, s51, 0x2000
	s_add_u32 s60, s42, 0x80000
	v_lshl_add_u64 v[220:221], s[42:43], 0, v[138:139]
	s_addc_u32 s61, s43, 0
	s_add_i32 s41, s41, s10
	global_load_lds_dwordx4 v[220:221], off
	v_lshl_add_u64 v[222:223], s[60:61], 0, v[0:1]
	s_mov_b32 m0, s41
	v_lshl_add_u64 v[224:225], s[58:59], 0, v[136:137]
	global_load_lds_dwordx4 v[222:223], off
	v_lshl_add_u64 v[222:223], s[60:61], 0, v[138:139]
	s_add_i32 m0, s41, 0x2000
	s_nop 0
	global_load_lds_dwordx4 v[222:223], off
	v_lshl_add_u64 v[222:223], s[58:59], 0, v[134:135]
	s_mov_b32 m0, s16
	s_nop 0
	global_load_lds_dwordx4 v[222:223], off
	s_mov_b32 m0, s17
	s_nop 0
	global_load_lds_dwordx4 v[224:225], off
	s_waitcnt vmcnt(8)
	s_waitcnt lgkmcnt(0)
	s_barrier
; #define PG8_STAGE(bufoff, gbase, voff) do { _Pragma("unroll") for (int _i = 0; _i < 2; ++_i) \
;         __builtin_amdgcn_global_load_lds((const unsigned*)((const char*)(gbase) + (voff)[_i]), (PG8_LAS unsigned*)(lds + (bufoff) + ldsw + _i * 8192), 16, 0, 0); } while (0)
; #define PG8_LDA(dst, b, h) do { _Pragma("unroll") for (int m = 0; m < 4; ++m) _Pragma("unroll") for (int k = 0; k < 2; ++k) dst[m][k] = *(const PG8_LAS bf16x8*)(lds + PG8_SA(b, h) + aoff + m * 2048 + k * 1024); } while (0)
; #define PG8_LDB(dst, b, h) do { _Pragma("unroll") for (int n = 0; n < 2; ++n) _Pragma("unroll") for (int k = 0; k < 2; ++k) dst[n][k] = *(const PG8_LAS bf16x8*)(lds + PG8_SB(b, h) + boff + n * 2048 + k * 1024); } while (0)
; #define PG8_MMA(ai, bj, At, Bt) do { __builtin_amdgcn_s_setprio(1); _Pragma("unroll") for (int m = 0; m < 4; ++m) _Pragma("unroll") for (int n = 0; n < 2; ++n) _Pragma("unroll") for (int k = 0; k < 2; ++k) \
;         acc[ai][bj][m][n] = __builtin_amdgcn_mfma_f32_16x16x32_bf16(Bt[n][k], At[m][k], acc[ai][bj][m][n], 0, 0, 0); __builtin_amdgcn_s_setprio(0); } while (0)
; #define PG8_WAIT_V(n) asm volatile("s_waitcnt vmcnt(" #n ")" ::: "memory")
; #define PG8_WAIT_L(n) asm volatile("s_waitcnt lgkmcnt(" #n ")" ::: "memory")
; #define PG8_BAR __builtin_amdgcn_s_barrier()
; #define PG8_SCHED __builtin_amdgcn_sched_barrier(0)
; template <class Epi, class Sched, bool ALIGN_EPI = false, bool SP2 = false>
; __device__ __forceinline__ void gemm_phase(PG8_LAS unsigned char* lds, const Gemm g, const Sched& S, const Epi& E) {
;     ...
;             PG8_WAIT_V(8); PG8_WAIT_L(0); PG8_BAR; PG8_MMA(1, 0, At, B0); PG8_MMA(1, 1, At, B1); PG8_BAR; PG8_SCHED;
;             PG8_LDB(B0, 1, 0); PG8_LDB(B1, 1, 1); PG8_SCHED; PG8_LDA(At, 1, 0); PG8_STAGE(PG8_SA(0, 1), a2 + hstep, voffA);
;             PG8_WAIT_V(8); PG8_WAIT_L(0); PG8_BAR; PG8_MMA(0, 0, At, B0); PG8_MMA(0, 1, At, B1); PG8_BAR; PG8_SCHED;
	s_setprio 1
	s_waitcnt lgkmcnt(0)
	v_mfma_f32_16x16x32_bf16 v[62:65], v[146:149], v[186:189], v[62:65]
	v_mfma_f32_16x16x32_bf16 v[58:61], v[160:163], v[186:189], v[58:61]
	v_mfma_f32_16x16x32_bf16 v[46:49], v[146:149], v[194:197], v[46:49]
	v_mfma_f32_16x16x32_bf16 v[42:45], v[160:163], v[194:197], v[42:45]
	v_mfma_f32_16x16x32_bf16 v[30:33], v[146:149], v[202:205], v[30:33]
	v_mfma_f32_16x16x32_bf16 v[26:29], v[160:163], v[202:205], v[26:29]
	v_mfma_f32_16x16x32_bf16 v[14:17], v[146:149], v[212:215], v[14:17]
	v_mfma_f32_16x16x32_bf16 v[10:13], v[160:163], v[212:215], v[10:13]
	v_mfma_f32_16x16x32_bf16 v[62:65], v[150:153], v[190:193], v[62:65]
	v_mfma_f32_16x16x32_bf16 v[58:61], v[164:167], v[190:193], v[58:61]
	v_mfma_f32_16x16x32_bf16 v[46:49], v[150:153], v[198:201], v[46:49]
	v_mfma_f32_16x16x32_bf16 v[42:45], v[164:167], v[198:201], v[42:45]
	v_mfma_f32_16x16x32_bf16 v[30:33], v[150:153], v[208:211], v[30:33]
	v_mfma_f32_16x16x32_bf16 v[26:29], v[164:167], v[208:211], v[26:29]
	v_mfma_f32_16x16x32_bf16 v[14:17], v[150:153], v[216:219], v[14:17]
	v_mfma_f32_16x16x32_bf16 v[10:13], v[164:167], v[216:219], v[10:13]
	v_mfma_f32_16x16x32_bf16 v[54:57], v[168:171], v[186:189], v[54:57]
	v_mfma_f32_16x16x32_bf16 v[50:53], v[176:179], v[186:189], v[50:53]
	v_mfma_f32_16x16x32_bf16 v[38:41], v[168:171], v[194:197], v[38:41]
	v_mfma_f32_16x16x32_bf16 v[34:37], v[176:179], v[194:197], v[34:37]
	v_mfma_f32_16x16x32_bf16 v[22:25], v[168:171], v[202:205], v[22:25]
	v_mfma_f32_16x16x32_bf16 v[18:21], v[176:179], v[202:205], v[18:21]
	v_mfma_f32_16x16x32_bf16 v[6:9], v[168:171], v[212:215], v[6:9]
	v_mfma_f32_16x16x32_bf16 v[2:5], v[176:179], v[212:215], v[2:5]
	v_mfma_f32_16x16x32_bf16 v[54:57], v[172:175], v[190:193], v[54:57]
	v_mfma_f32_16x16x32_bf16 v[50:53], v[180:183], v[190:193], v[50:53]
	v_mfma_f32_16x16x32_bf16 v[38:41], v[172:175], v[198:201], v[38:41]
	v_mfma_f32_16x16x32_bf16 v[34:37], v[180:183], v[198:201], v[34:37]
	v_mfma_f32_16x16x32_bf16 v[22:25], v[172:175], v[208:211], v[22:25]
	v_mfma_f32_16x16x32_bf16 v[18:21], v[180:183], v[208:211], v[18:21]
	v_mfma_f32_16x16x32_bf16 v[6:9], v[172:175], v[216:219], v[6:9]
	v_mfma_f32_16x16x32_bf16 v[2:5], v[180:183], v[216:219], v[2:5]
	s_setprio 0
	s_barrier
	s_add_i32 s41, 0, 0x18000
	s_add_i32 s51, 0, 0x1c000
	v_add_u32_e32 v164, s41, v157
	v_add_u32_e32 v180, s51, v157
	ds_read_b128 v[146:149], v164
	ds_read_b128 v[150:153], v164 offset:1024
	ds_read_b128 v[160:163], v164 offset:2048
	ds_read_b128 v[164:167], v164 offset:3072
	ds_read_b128 v[168:171], v180
	ds_read_b128 v[172:175], v180 offset:1024
	ds_read_b128 v[176:179], v180 offset:2048
	ds_read_b128 v[180:183], v180 offset:3072
	s_add_u32 s58, s58, 0x80000
	s_addc_u32 s59, s59, 0
	s_mov_b32 m0, s25
	v_lshl_add_u64 v[226:227], s[58:59], 0, v[134:135]
	ds_read_b128 v[186:189], v159 offset:32768
	ds_read_b128 v[190:193], v159 offset:33792
	ds_read_b128 v[194:197], v159 offset:34816
	ds_read_b128 v[198:201], v159 offset:35840
	ds_read_b128 v[202:205], v159 offset:36864
	ds_read_b128 v[208:211], v159 offset:37888
	ds_read_b128 v[212:215], v159 offset:38912
	ds_read_b128 v[216:219], v159 offset:39936
	global_load_lds_dwordx4 v[226:227], off
	v_lshl_add_u64 v[226:227], s[58:59], 0, v[136:137]
	s_mov_b32 m0, s30
	s_nop 0
	global_load_lds_dwordx4 v[226:227], off
	s_waitcnt vmcnt(8)
	s_waitcnt lgkmcnt(0)
	s_barrier
	s_setprio 1
	s_waitcnt lgkmcnt(0)
	v_mfma_f32_16x16x32_bf16 v[130:133], v[146:149], v[186:189], v[130:133]
	v_mfma_f32_16x16x32_bf16 v[126:129], v[160:163], v[186:189], v[126:129]
	v_mfma_f32_16x16x32_bf16 v[114:117], v[146:149], v[194:197], v[114:117]
	v_mfma_f32_16x16x32_bf16 v[110:113], v[160:163], v[194:197], v[110:113]
	v_mfma_f32_16x16x32_bf16 v[94:97], v[146:149], v[202:205], v[94:97]
	v_mfma_f32_16x16x32_bf16 v[90:93], v[160:163], v[202:205], v[90:93]
	v_mfma_f32_16x16x32_bf16 v[78:81], v[146:149], v[212:215], v[78:81]
	v_mfma_f32_16x16x32_bf16 v[74:77], v[160:163], v[212:215], v[74:77]
	v_mfma_f32_16x16x32_bf16 v[130:133], v[150:153], v[190:193], v[130:133]
	v_mfma_f32_16x16x32_bf16 v[126:129], v[164:167], v[190:193], v[126:129]
	v_mfma_f32_16x16x32_bf16 v[114:117], v[150:153], v[198:201], v[114:117]
	v_mfma_f32_16x16x32_bf16 v[110:113], v[164:167], v[198:201], v[110:113]
	v_mfma_f32_16x16x32_bf16 v[94:97], v[150:153], v[208:211], v[94:97]
	v_mfma_f32_16x16x32_bf16 v[90:93], v[164:167], v[208:211], v[90:93]
	v_mfma_f32_16x16x32_bf16 v[78:81], v[150:153], v[216:219], v[78:81]
	v_mfma_f32_16x16x32_bf16 v[74:77], v[164:167], v[216:219], v[74:77]
	v_mfma_f32_16x16x32_bf16 v[122:125], v[168:171], v[186:189], v[122:125]
	v_mfma_f32_16x16x32_bf16 v[118:121], v[176:179], v[186:189], v[118:121]
	v_mfma_f32_16x16x32_bf16 v[106:109], v[168:171], v[194:197], v[106:109]
	v_mfma_f32_16x16x32_bf16 v[102:105], v[176:179], v[194:197], v[102:105]
	v_mfma_f32_16x16x32_bf16 v[86:89], v[168:171], v[202:205], v[86:89]
	v_mfma_f32_16x16x32_bf16 v[82:85], v[176:179], v[202:205], v[82:85]
	v_mfma_f32_16x16x32_bf16 v[70:73], v[168:171], v[212:215], v[70:73]
	v_mfma_f32_16x16x32_bf16 v[66:69], v[176:179], v[212:215], v[66:69]
	v_mfma_f32_16x16x32_bf16 v[122:125], v[172:175], v[190:193], v[122:125]
	v_mfma_f32_16x16x32_bf16 v[118:121], v[180:183], v[190:193], v[118:121]
	v_mfma_f32_16x16x32_bf16 v[106:109], v[172:175], v[198:201], v[106:109]
	v_mfma_f32_16x16x32_bf16 v[102:105], v[180:183], v[198:201], v[102:105]
	v_mfma_f32_16x16x32_bf16 v[86:89], v[172:175], v[208:211], v[86:89]
	v_mfma_f32_16x16x32_bf16 v[82:85], v[180:183], v[208:211], v[82:85]
	v_mfma_f32_16x16x32_bf16 v[70:73], v[172:175], v[216:219], v[70:73]
	v_mfma_f32_16x16x32_bf16 v[66:69], v[180:183], v[216:219], v[66:69]
	s_setprio 0
	s_barrier
; #define PG8_STAGE(bufoff, gbase, voff) do { _Pragma("unroll") for (int _i = 0; _i < 2; ++_i) \
;         __builtin_amdgcn_global_load_lds((const unsigned*)((const char*)(gbase) + (voff)[_i]), (PG8_LAS unsigned*)(lds + (bufoff) + ldsw + _i * 8192), 16, 0, 0); } while (0)
; #define PG8_LDA(dst, b, h) do { _Pragma("unroll") for (int m = 0; m < 4; ++m) _Pragma("unroll") for (int k = 0; k < 2; ++k) dst[m][k] = *(const PG8_LAS bf16x8*)(lds + PG8_SA(b, h) + aoff + m * 2048 + k * 1024); } while (0)
; #define PG8_MMA(ai, bj, At, Bt) do { __builtin_amdgcn_s_setprio(1); _Pragma("unroll") for (int m = 0; m < 4; ++m) _Pragma("unroll") for (int n = 0; n < 2; ++n) _Pragma("unroll") for (int k = 0; k < 2; ++k) \
;         acc[ai][bj][m][n] = __builtin_amdgcn_mfma_f32_16x16x32_bf16(Bt[n][k], At[m][k], acc[ai][bj][m][n], 0, 0, 0); __builtin_amdgcn_s_setprio(0); } while (0)
; #define PG8_WAIT_V(n) asm volatile("s_waitcnt vmcnt(" #n ")" ::: "memory")
; #define PG8_WAIT_L(n) asm volatile("s_waitcnt lgkmcnt(" #n ")" ::: "memory")
; #define PG8_BAR __builtin_amdgcn_s_barrier()
; #define PG8_SCHED __builtin_amdgcn_sched_barrier(0)
; template <class Epi, class Sched, bool ALIGN_EPI = false, bool SP2 = false>
; __device__ __forceinline__ void gemm_phase(PG8_LAS unsigned char* lds, const Gemm g, const Sched& S, const Epi& E) {
;     ...
;         for (int t = 0; t < nt; t += 2) {
;             const bool last = (t == nt - 2);
;     ...
;             PG8_LDA(At, 1, 1); PG8_STAGE(PG8_SB(1, 0), b3, voffB); PG8_STAGE(PG8_SB(1, 1), b3 + hstep, voffB); PG8_STAGE(PG8_SA(1, 0), a3, voffA);
;             PG8_WAIT_V(8); PG8_WAIT_L(0); PG8_BAR; PG8_MMA(1, 0, At, B0); PG8_MMA(1, 1, At, B1); PG8_BAR; PG8_SCHED;
	s_add_i32 s41, s41, s10
	v_lshl_add_u64 v[154:155], v[154:155], 0, s[22:23]
	s_mov_b32 m0, s41
	ds_read_b128 v[186:189], v159 offset:49152
	ds_read_b128 v[190:193], v159 offset:50176
	ds_read_b128 v[194:197], v159 offset:51200
	ds_read_b128 v[198:201], v159 offset:52224
	ds_read_b128 v[202:205], v159 offset:53248
	ds_read_b128 v[208:211], v159 offset:54272
	ds_read_b128 v[212:215], v159 offset:55296
	ds_read_b128 v[216:219], v159 offset:56320
	global_load_lds_dwordx4 v[154:155], off
	s_add_i32 m0, s41, 0x2000
	s_add_u32 s42, s42, 0x80080
	v_lshl_add_u64 v[154:155], v[220:221], 0, s[22:23]
	s_addc_u32 s43, s43, 0
	s_add_i32 s41, s51, s10
	global_load_lds_dwordx4 v[154:155], off
	v_lshl_add_u64 v[154:155], s[42:43], 0, v[0:1]
	s_mov_b32 m0, s41
	s_nop 0
	global_load_lds_dwordx4 v[154:155], off
	v_lshl_add_u64 v[154:155], s[42:43], 0, v[138:139]
	s_add_i32 m0, s41, 0x2000
	s_nop 0
	global_load_lds_dwordx4 v[154:155], off
	v_lshl_add_u64 v[154:155], v[222:223], 0, s[22:23]
	s_mov_b32 m0, s9
	s_nop 0
	global_load_lds_dwordx4 v[154:155], off
	v_lshl_add_u64 v[154:155], v[224:225], 0, s[22:23]
	s_mov_b32 m0, s15
	s_nop 0
	global_load_lds_dwordx4 v[154:155], off
	s_waitcnt vmcnt(8)
	s_waitcnt lgkmcnt(0)
	s_barrier
	s_setprio 1
	s_waitcnt lgkmcnt(0)
	v_mfma_f32_16x16x32_bf16 v[62:65], v[146:149], v[186:189], v[62:65]
	v_mfma_f32_16x16x32_bf16 v[58:61], v[160:163], v[186:189], v[58:61]
	v_mfma_f32_16x16x32_bf16 v[46:49], v[146:149], v[194:197], v[46:49]
	v_mfma_f32_16x16x32_bf16 v[42:45], v[160:163], v[194:197], v[42:45]
	v_mfma_f32_16x16x32_bf16 v[30:33], v[146:149], v[202:205], v[30:33]
	v_mfma_f32_16x16x32_bf16 v[26:29], v[160:163], v[202:205], v[26:29]
	v_mfma_f32_16x16x32_bf16 v[14:17], v[146:149], v[212:215], v[14:17]
	v_mfma_f32_16x16x32_bf16 v[10:13], v[160:163], v[212:215], v[10:13]
	v_mfma_f32_16x16x32_bf16 v[62:65], v[150:153], v[190:193], v[62:65]
	v_mfma_f32_16x16x32_bf16 v[58:61], v[164:167], v[190:193], v[58:61]
	v_mfma_f32_16x16x32_bf16 v[46:49], v[150:153], v[198:201], v[46:49]
	v_mfma_f32_16x16x32_bf16 v[42:45], v[164:167], v[198:201], v[42:45]
	v_mfma_f32_16x16x32_bf16 v[30:33], v[150:153], v[208:211], v[30:33]
	v_mfma_f32_16x16x32_bf16 v[26:29], v[164:167], v[208:211], v[26:29]
	v_mfma_f32_16x16x32_bf16 v[14:17], v[150:153], v[216:219], v[14:17]
	v_mfma_f32_16x16x32_bf16 v[10:13], v[164:167], v[216:219], v[10:13]
	v_mfma_f32_16x16x32_bf16 v[54:57], v[168:171], v[186:189], v[54:57]
	v_mfma_f32_16x16x32_bf16 v[50:53], v[176:179], v[186:189], v[50:53]
	v_mfma_f32_16x16x32_bf16 v[38:41], v[168:171], v[194:197], v[38:41]
	v_mfma_f32_16x16x32_bf16 v[34:37], v[176:179], v[194:197], v[34:37]
	v_mfma_f32_16x16x32_bf16 v[22:25], v[168:171], v[202:205], v[22:25]
	v_mfma_f32_16x16x32_bf16 v[18:21], v[176:179], v[202:205], v[18:21]
	v_mfma_f32_16x16x32_bf16 v[6:9], v[168:171], v[212:215], v[6:9]
	v_mfma_f32_16x16x32_bf16 v[2:5], v[176:179], v[212:215], v[2:5]
	v_mfma_f32_16x16x32_bf16 v[54:57], v[172:175], v[190:193], v[54:57]
	v_mfma_f32_16x16x32_bf16 v[50:53], v[180:183], v[190:193], v[50:53]
	v_mfma_f32_16x16x32_bf16 v[38:41], v[172:175], v[198:201], v[38:41]
	v_mfma_f32_16x16x32_bf16 v[34:37], v[180:183], v[198:201], v[34:37]
	v_mfma_f32_16x16x32_bf16 v[22:25], v[172:175], v[208:211], v[22:25]
	v_mfma_f32_16x16x32_bf16 v[18:21], v[180:183], v[208:211], v[18:21]
	v_mfma_f32_16x16x32_bf16 v[6:9], v[172:175], v[216:219], v[6:9]
	v_mfma_f32_16x16x32_bf16 v[2:5], v[180:183], v[216:219], v[2:5]
	s_setprio 0
	s_barrier
	s_add_i32 s19, s19, 2
	s_add_u32 s14, s14, 0x100
	s_addc_u32 s18, s18, 0
	s_add_u32 s0, s0, 0x100
	s_addc_u32 s1, s1, 0
	s_cmp_gt_u32 s19, 29
	s_cbranch_scc0 .LBB0_1272
	s_and_b64 vcc, exec, s[48:49]
	s_cbranch_vccz .LBB0_1275
	s_barrier
